# up-proj epilogue: conv weight/bias loads issued before the LDS staging of the u tile
# speedup vs baseline: 1.0053x; 1.0053x over previous
.LBB0_84:
	v_and_b32_e32 v0, 15, v140
	v_lshrrev_b32_e32 v130, 2, v140
	s_mov_b32 s1, 0xfffffc0
	v_and_or_b32 v130, v130, s1, v0
	v_and_b32_e32 v131, 0xc0, v140
	s_movk_i32 s1, 0x210
	v_add_u32_e32 v131, 0, v131
	v_and_b32_e32 v132, 48, v140
	v_mul_lo_u32 v130, v130, s1
	v_add3_u32 v130, v131, v132, v130
	v_cvt_pk_bf16_f32 v62, v62, v63
	v_cvt_pk_bf16_f32 v63, v64, v65
	v_cvt_pk_bf16_f32 v64, v58, v59
	v_add_u32_e32 v58, 0x10900, v130
	v_cvt_pk_bf16_f32 v46, v46, v47
	v_cvt_pk_bf16_f32 v47, v48, v49
	v_cvt_pk_bf16_f32 v48, v42, v43
	v_cvt_pk_bf16_f32 v49, v44, v45
	s_barrier
	s_waitcnt vmcnt(0)
	v_and_b32_e32 v240, 15, v140
	v_lshlrev_b32_e32 v240, 3, v240
	v_or_b32_e32 v240, s2, v240
	v_lshlrev_b32_e32 v240, 2, v240
	global_load_dwordx4 v[144:147], v240, s[52:53] offset:16
	global_load_dwordx4 v[148:151], v240, s[52:53]
	global_load_dwordx4 v[152:155], v240, s[8:9] offset:16
	global_load_dwordx4 v[158:161], v240, s[8:9]
	global_load_dwordx4 v[162:165], v240, s[18:19] offset:16
	global_load_dwordx4 v[196:199], v240, s[18:19]
	global_load_dwordx4 v[200:203], v240, s[62:63] offset:16
	global_load_dwordx4 v[204:207], v240, s[62:63]
	global_load_dwordx4 v[208:211], v240, s[48:49] offset:16
	global_load_dwordx4 v[212:215], v240, s[48:49]
	global_load_dwordx4 v[216:219], v240, s[46:47] offset:16
	global_load_dwordx4 v[220:223], v240, s[46:47]
	global_load_dwordx4 v[224:227], v240, s[56:57] offset:16
	global_load_dwordx4 v[228:231], v240, s[56:57]
	global_load_dwordx4 v[232:235], v240, s[88:89] offset:16
	global_load_dwordx4 v[236:239], v240, s[88:89]
	ds_write_b128 v58, v[46:49]
	v_add_u32_e32 v46, 0x12900, v130
	v_cvt_pk_bf16_f32 v42, v54, v55
	v_cvt_pk_bf16_f32 v43, v56, v57
	v_cvt_pk_bf16_f32 v44, v50, v51
	v_cvt_pk_bf16_f32 v45, v52, v53
	ds_write_b128 v46, v[42:45]
	v_add_u32_e32 v42, 0x12a00, v130
	v_cvt_pk_bf16_f32 v30, v30, v31
	v_cvt_pk_bf16_f32 v31, v32, v33
	v_cvt_pk_bf16_f32 v32, v26, v27
	v_cvt_pk_bf16_f32 v33, v28, v29
	v_cvt_pk_bf16_f32 v70, v70, v71
	v_cvt_pk_bf16_f32 v71, v72, v73
	v_cvt_pk_bf16_f32 v72, v66, v67
	v_add_u32_e32 v66, 0x10800, v130
	v_cvt_pk_bf16_f32 v65, v60, v61
	ds_write_b128 v42, v[30:33]
	v_add_u32_e32 v30, 0x14a00, v130
	v_cvt_pk_bf16_f32 v26, v38, v39
	v_cvt_pk_bf16_f32 v27, v40, v41
	v_cvt_pk_bf16_f32 v28, v34, v35
	v_cvt_pk_bf16_f32 v29, v36, v37
	v_lshlrev_b32_e32 v0, 3, v0
	ds_write_b128 v66, v[62:65]
	ds_write_b128 v30, v[26:29]
	v_add_u32_e32 v26, 0x14b00, v130
	v_cvt_pk_bf16_f32 v14, v14, v15
	v_cvt_pk_bf16_f32 v15, v16, v17
	v_cvt_pk_bf16_f32 v16, v10, v11
	v_cvt_pk_bf16_f32 v17, v12, v13
	v_or_b32_e32 v66, s2, v0
	ds_write_b128 v26, v[14:17]
	v_add_u32_e32 v14, 0x16b00, v130
	v_cvt_pk_bf16_f32 v10, v22, v23
	v_cvt_pk_bf16_f32 v11, v24, v25
	v_cvt_pk_bf16_f32 v12, v18, v19
	v_cvt_pk_bf16_f32 v13, v20, v21
	v_ashrrev_i32_e32 v67, 31, v66
	ds_write_b128 v14, v[10:13]
	v_add_u32_e32 v10, 0x16c00, v130
	v_cvt_pk_bf16_f32 v6, v6, v7
	v_cvt_pk_bf16_f32 v7, v8, v9
	v_cvt_pk_bf16_f32 v8, v2, v3
	v_cvt_pk_bf16_f32 v9, v4, v5
	v_lshlrev_b64 v[2:3], 2, v[66:67]
	v_cvt_pk_bf16_f32 v126, v126, v127
	v_cvt_pk_bf16_f32 v127, v128, v129
	v_cvt_pk_bf16_f32 v128, v122, v123
	v_cvt_pk_bf16_f32 v129, v124, v125
	v_cvt_pk_bf16_f32 v110, v110, v111
	v_cvt_pk_bf16_f32 v111, v112, v113
	v_cvt_pk_bf16_f32 v112, v106, v107
	v_cvt_pk_bf16_f32 v113, v108, v109
	v_cvt_pk_bf16_f32 v106, v118, v119
	v_cvt_pk_bf16_f32 v107, v120, v121
	v_cvt_pk_bf16_f32 v108, v114, v115
	v_cvt_pk_bf16_f32 v109, v116, v117
	v_cvt_pk_bf16_f32 v94, v94, v95
	v_cvt_pk_bf16_f32 v95, v96, v97
	v_cvt_pk_bf16_f32 v96, v90, v91
	v_cvt_pk_bf16_f32 v97, v92, v93
	v_cvt_pk_bf16_f32 v90, v102, v103
	v_cvt_pk_bf16_f32 v91, v104, v105
	v_cvt_pk_bf16_f32 v92, v98, v99
	v_cvt_pk_bf16_f32 v93, v100, v101
	v_cvt_pk_bf16_f32 v78, v78, v79
	v_cvt_pk_bf16_f32 v79, v80, v81
	v_cvt_pk_bf16_f32 v80, v74, v75
	v_cvt_pk_bf16_f32 v81, v76, v77
	v_cvt_pk_bf16_f32 v74, v86, v87
	v_cvt_pk_bf16_f32 v75, v88, v89
	v_cvt_pk_bf16_f32 v76, v82, v83
	v_cvt_pk_bf16_f32 v77, v84, v85
	v_cvt_pk_bf16_f32 v73, v68, v69
	ds_write_b128 v10, v[6:9]
	v_lshl_add_u64 v[6:7], s[52:53], 0, v[2:3]
	v_lshl_add_u64 v[8:9], s[8:9], 0, v[2:3]
	v_lshl_add_u64 v[10:11], s[18:19], 0, v[2:3]
	v_lshl_add_u64 v[12:13], s[62:63], 0, v[2:3]
	v_lshl_add_u64 v[14:15], s[48:49], 0, v[2:3]
	v_lshl_add_u64 v[16:17], s[46:47], 0, v[2:3]
	v_lshl_add_u64 v[30:31], s[56:57], 0, v[2:3]
	v_lshl_add_u64 v[62:63], s[88:89], 0, v[2:3]
	ds_write_b128 v130, v[126:129]
	ds_write_b128 v130, v[110:113] offset:256
	ds_write_b128 v130, v[106:109] offset:8448
	ds_write_b128 v130, v[94:97] offset:8704
	ds_write_b128 v130, v[90:93] offset:16896
	ds_write_b128 v130, v[78:81] offset:17152
	ds_write_b128 v130, v[74:77] offset:25344
	ds_write_b128 v130, v[70:73] offset:25600
	s_waitcnt lgkmcnt(0)
	s_barrier
	s_waitcnt vmcnt(0)
	v_mov_b64_e32 v[2:3], v[144:145]
	v_mov_b64_e32 v[4:5], v[146:147]
	v_mov_b64_e32 v[34:35], v[148:149]
	v_mov_b64_e32 v[36:37], v[150:151]
	v_mov_b64_e32 v[18:19], v[152:153]
	v_mov_b64_e32 v[20:21], v[154:155]
	v_mov_b64_e32 v[50:51], v[158:159]
	v_mov_b64_e32 v[52:53], v[160:161]
	v_mov_b64_e32 v[6:7], v[162:163]
	v_mov_b64_e32 v[8:9], v[164:165]
	v_mov_b64_e32 v[38:39], v[196:197]
	v_mov_b64_e32 v[40:41], v[198:199]
	v_mov_b64_e32 v[22:23], v[200:201]
	v_mov_b64_e32 v[24:25], v[202:203]
	v_mov_b64_e32 v[54:55], v[204:205]
	v_mov_b64_e32 v[56:57], v[206:207]
	v_mov_b64_e32 v[10:11], v[208:209]
	v_mov_b64_e32 v[12:13], v[210:211]
	v_mov_b64_e32 v[42:43], v[212:213]
	v_mov_b64_e32 v[44:45], v[214:215]
	v_mov_b64_e32 v[26:27], v[216:217]
	v_mov_b64_e32 v[28:29], v[218:219]
	v_mov_b64_e32 v[58:59], v[220:221]
	v_mov_b64_e32 v[60:61], v[222:223]
	v_mov_b64_e32 v[14:15], v[224:225]
	v_mov_b64_e32 v[16:17], v[226:227]
	v_mov_b64_e32 v[46:47], v[228:229]
	v_mov_b64_e32 v[48:49], v[230:231]
	v_mov_b64_e32 v[30:31], v[232:233]
	v_mov_b64_e32 v[32:33], v[234:235]
	v_mov_b64_e32 v[62:63], v[236:237]
	v_mov_b64_e32 v[64:65], v[238:239]
	v_ashrrev_i32_e32 v128, 4, v140
	v_lshlrev_b32_e32 v129, 3, v128
	v_add_u32_e32 v68, -1, v129
	s_movk_i32 s1, 0x100
	v_cmp_gt_u32_e32 vcc, s1, v68
	v_mov_b32_e32 v78, 0
	v_lshlrev_b32_e32 v0, 1, v0
	v_mov_b32_e32 v72, 0
	v_mov_b32_e32 v73, 0
	v_mov_b32_e32 v92, 0
	v_mov_b32_e32 v93, 0
	v_mov_b32_e32 v90, 0
	v_mov_b32_e32 v91, 0
	v_mov_b32_e32 v102, 0
	v_mov_b32_e32 v103, 0
	v_mov_b32_e32 v96, 0
	v_mov_b32_e32 v97, 0
	v_mov_b32_e32 v114, 0
	v_mov_b32_e32 v115, 0
	v_mov_b32_e32 v108, 0
	v_mov_b32_e32 v109, 0
	v_mov_b32_e32 v116, 0
	v_mov_b32_e32 v117, 0
	s_and_saveexec_b64 s[2:3], vcc
	s_movk_i32 s83, 0x2000
	s_movk_i32 s86, 0x1fff
	s_mov_b32 s70, 0x800000
	s_mov_b32 s87, 0xc000
	s_movk_i32 s58, 0x21ff
	s_cbranch_execz .LBB0_86
	s_movk_i32 s16, 0x210
	v_mul_lo_u32 v68, v68, s16
	v_add3_u32 v72, 0, v68, v0
	ds_read_b128 v[68:71], v72
	ds_read_b128 v[74:77], v72 offset:256
	s_waitcnt lgkmcnt(1)
	v_lshlrev_b32_e32 v108, 16, v68
	v_and_b32_e32 v109, 0xffff0000, v68
	v_lshlrev_b32_e32 v96, 16, v69
	v_and_b32_e32 v97, 0xffff0000, v69
	v_lshlrev_b32_e32 v90, 16, v70
	v_and_b32_e32 v91, 0xffff0000, v70
	v_lshlrev_b32_e32 v72, 16, v71
	v_and_b32_e32 v73, 0xffff0000, v71
	s_waitcnt lgkmcnt(0)
	v_lshlrev_b32_e32 v116, 16, v74
	v_and_b32_e32 v117, 0xffff0000, v74
	v_lshlrev_b32_e32 v114, 16, v75
	v_and_b32_e32 v115, 0xffff0000, v75
	v_lshlrev_b32_e32 v102, 16, v76
	v_and_b32_e32 v103, 0xffff0000, v76
	v_lshlrev_b32_e32 v92, 16, v77
	v_and_b32_e32 v93, 0xffff0000, v77
